# P9 (fp8 SwiGLU) epilogue: the 8 serialized ssq row-scale loads (each load; vmcnt(0); compute; store) hoisted and issued together, one wait
# speedup vs baseline: 1.0090x; 1.0090x over previous
.LBB0_633:
	v_lshl_add_u32 v0, s6, 8, v194
	v_ashrrev_i32_e32 v1, 31, v0
	v_lshl_add_u64 v[0:1], v[0:1], 2, s[12:13]
	global_load_dword v220, v[0:1], off
	global_load_dword v221, v[0:1], off offset:64
	global_load_dword v222, v[0:1], off offset:128
	global_load_dword v223, v[0:1], off offset:192
	global_load_dword v224, v[0:1], off offset:512
	global_load_dword v225, v[0:1], off offset:576
	global_load_dword v226, v[0:1], off offset:640
	global_load_dword v227, v[0:1], off offset:704
	s_lshl_b32 s0, s7, 7
	s_or_b32 s0, s0, s83
	s_ashr_i32 s0, s0, 6
	s_mul_hi_i32 s1, s6, 0x56
	s_mulk_i32 s6, 0x56
	s_ashr_i32 s7, s0, 31
	s_add_u32 s0, s6, s0
	s_addc_u32 s1, s1, s7
	v_pk_mul_f32 v[4:5], v[152:153], v[156:157]
	s_lshl_b64 s[0:1], s[0:1], 15
	v_pk_mul_f32 v[2:3], v[154:155], v[158:159]
	v_pk_mul_f32 v[6:7], v[150:151], v[146:147]
	v_pk_mul_f32 v[8:9], v[148:149], v[144:145]
	s_waitcnt vmcnt(0)
	v_fmamk_f32 v10, v220, 0x3a000000, v200
	v_mul_f32_e32 v11, 0x4b800000, v10
	v_cmp_gt_f32_e32 vcc, s51, v10
	s_nop 1
	v_cndmask_b32_e32 v10, v10, v11, vcc
	v_rsq_f32_e32 v12, v10
	v_lshl_add_u64 v[10:11], v[170:171], 0, s[0:1]
	v_mul_f32_e32 v13, 0x45800000, v12
	v_cndmask_b32_e32 v12, v12, v13, vcc
	v_mul_f32_e32 v13, 0x3b800000, v12
	v_mul_f32_e32 v12, 0xbfb8aa3b, v13
	v_pk_mul_f32 v[16:17], v[152:153], v[12:13] op_sel_hi:[1,0]
	v_mul_f32_e32 v14, v13, v13
	v_pk_mul_f32 v[18:19], v[154:155], v[12:13] op_sel_hi:[1,0]
	v_pk_mul_f32 v[20:21], v[148:149], v[12:13] op_sel_hi:[1,0]
	v_pk_mul_f32 v[12:13], v[150:151], v[12:13] op_sel_hi:[1,0]
	v_exp_f32_e32 v16, v16
	v_exp_f32_e32 v17, v17
	v_exp_f32_e32 v18, v18
	v_exp_f32_e32 v19, v19
	v_exp_f32_e32 v20, v20
	v_exp_f32_e32 v21, v21
	v_exp_f32_e32 v12, v12
	v_exp_f32_e32 v13, v13
	v_pk_add_f32 v[16:17], v[16:17], 1.0 op_sel_hi:[1,0]
	v_pk_add_f32 v[18:19], v[18:19], 1.0 op_sel_hi:[1,0]
	v_pk_add_f32 v[20:21], v[20:21], 1.0 op_sel_hi:[1,0]
	v_pk_add_f32 v[12:13], v[12:13], 1.0 op_sel_hi:[1,0]
	v_rcp_f32_e32 v16, v16
	v_rcp_f32_e32 v17, v17
	v_rcp_f32_e32 v18, v18
	v_rcp_f32_e32 v19, v19
	v_rcp_f32_e32 v20, v20
	v_rcp_f32_e32 v21, v21
	v_rcp_f32_e32 v12, v12
	v_rcp_f32_e32 v13, v13
	v_pk_mul_f32 v[16:17], v[14:15], v[16:17] op_sel_hi:[0,1]
	v_pk_mul_f32 v[18:19], v[14:15], v[18:19] op_sel_hi:[0,1]
	v_pk_mul_f32 v[20:21], v[14:15], v[20:21] op_sel_hi:[0,1]
	v_pk_mul_f32 v[12:13], v[14:15], v[12:13] op_sel_hi:[0,1]
	v_pk_mul_f32 v[4:5], v[4:5], v[16:17]
	v_pk_mul_f32 v[14:15], v[2:3], v[18:19]
	v_pk_mul_f32 v[8:9], v[8:9], v[20:21]
	v_pk_mul_f32 v[6:7], v[6:7], v[12:13]
	v_cvt_pk_bf16_f32 v2, v4, v5
	v_cvt_pk_bf16_f32 v3, v14, v15
	v_cvt_pk_bf16_f32 v4, v8, v9
	v_pk_mul_f32 v[8:9], v[132:133], v[128:129]
	v_cvt_pk_bf16_f32 v5, v6, v7
	global_store_dwordx4 v[10:11], v[2:5], off nt
	s_nop 0
	v_lshl_add_u64 v[10:11], v[172:173], 0, s[0:1]
	v_pk_mul_f32 v[4:5], v[136:137], v[140:141]
	v_pk_mul_f32 v[2:3], v[138:139], v[142:143]
	v_fmamk_f32 v6, v221, 0x3a000000, v200
	v_mul_f32_e32 v7, 0x4b800000, v6
	v_cmp_gt_f32_e32 vcc, s51, v6
	s_nop 1
	v_cndmask_b32_e32 v6, v6, v7, vcc
	v_rsq_f32_e32 v12, v6
	v_pk_mul_f32 v[6:7], v[134:135], v[130:131]
	v_mul_f32_e32 v13, 0x45800000, v12
	v_cndmask_b32_e32 v12, v12, v13, vcc
	v_mul_f32_e32 v13, 0x3b800000, v12
	v_mul_f32_e32 v12, 0xbfb8aa3b, v13
	v_pk_mul_f32 v[16:17], v[136:137], v[12:13] op_sel_hi:[1,0]
	v_mul_f32_e32 v14, v13, v13
	v_pk_mul_f32 v[18:19], v[138:139], v[12:13] op_sel_hi:[1,0]
	v_pk_mul_f32 v[20:21], v[132:133], v[12:13] op_sel_hi:[1,0]
	v_pk_mul_f32 v[12:13], v[134:135], v[12:13] op_sel_hi:[1,0]
	v_exp_f32_e32 v16, v16
	v_exp_f32_e32 v17, v17
	v_exp_f32_e32 v18, v18
	v_exp_f32_e32 v19, v19
	v_exp_f32_e32 v20, v20
	v_exp_f32_e32 v21, v21
	v_exp_f32_e32 v12, v12
	v_exp_f32_e32 v13, v13
	v_pk_add_f32 v[16:17], v[16:17], 1.0 op_sel_hi:[1,0]
	v_pk_add_f32 v[18:19], v[18:19], 1.0 op_sel_hi:[1,0]
	v_pk_add_f32 v[20:21], v[20:21], 1.0 op_sel_hi:[1,0]
	v_pk_add_f32 v[12:13], v[12:13], 1.0 op_sel_hi:[1,0]
	v_rcp_f32_e32 v16, v16
	v_rcp_f32_e32 v17, v17
	v_rcp_f32_e32 v18, v18
	v_rcp_f32_e32 v19, v19
	v_rcp_f32_e32 v20, v20
	v_rcp_f32_e32 v21, v21
	v_rcp_f32_e32 v12, v12
	v_rcp_f32_e32 v13, v13
	v_pk_mul_f32 v[16:17], v[14:15], v[16:17] op_sel_hi:[0,1]
	v_pk_mul_f32 v[18:19], v[14:15], v[18:19] op_sel_hi:[0,1]
	v_pk_mul_f32 v[20:21], v[14:15], v[20:21] op_sel_hi:[0,1]
	v_pk_mul_f32 v[12:13], v[14:15], v[12:13] op_sel_hi:[0,1]
	v_pk_mul_f32 v[4:5], v[4:5], v[16:17]
	v_pk_mul_f32 v[14:15], v[2:3], v[18:19]
	v_pk_mul_f32 v[8:9], v[8:9], v[20:21]
	v_pk_mul_f32 v[6:7], v[6:7], v[12:13]
	v_cvt_pk_bf16_f32 v2, v4, v5
	v_cvt_pk_bf16_f32 v3, v14, v15
	v_cvt_pk_bf16_f32 v4, v8, v9
	v_pk_mul_f32 v[8:9], v[116:117], v[112:113]
	v_cvt_pk_bf16_f32 v5, v6, v7
	global_store_dwordx4 v[10:11], v[2:5], off nt
	s_nop 0
	v_lshl_add_u64 v[10:11], v[174:175], 0, s[0:1]
	v_pk_mul_f32 v[4:5], v[120:121], v[124:125]
	v_pk_mul_f32 v[2:3], v[122:123], v[126:127]
	v_fmamk_f32 v6, v222, 0x3a000000, v200
	v_mul_f32_e32 v7, 0x4b800000, v6
	v_cmp_gt_f32_e32 vcc, s51, v6
	s_nop 1
	v_cndmask_b32_e32 v6, v6, v7, vcc
	v_rsq_f32_e32 v12, v6
	v_pk_mul_f32 v[6:7], v[118:119], v[114:115]
	v_mul_f32_e32 v13, 0x45800000, v12
	v_cndmask_b32_e32 v12, v12, v13, vcc
	v_mul_f32_e32 v13, 0x3b800000, v12
	v_mul_f32_e32 v12, 0xbfb8aa3b, v13
	v_pk_mul_f32 v[16:17], v[120:121], v[12:13] op_sel_hi:[1,0]
	v_mul_f32_e32 v14, v13, v13
	v_pk_mul_f32 v[18:19], v[122:123], v[12:13] op_sel_hi:[1,0]
	v_pk_mul_f32 v[20:21], v[116:117], v[12:13] op_sel_hi:[1,0]
	v_pk_mul_f32 v[12:13], v[118:119], v[12:13] op_sel_hi:[1,0]
	v_exp_f32_e32 v16, v16
	v_exp_f32_e32 v17, v17
	v_exp_f32_e32 v18, v18
	v_exp_f32_e32 v19, v19
	v_exp_f32_e32 v20, v20
	v_exp_f32_e32 v21, v21
	v_exp_f32_e32 v12, v12
	v_exp_f32_e32 v13, v13
	v_pk_add_f32 v[16:17], v[16:17], 1.0 op_sel_hi:[1,0]
	v_pk_add_f32 v[18:19], v[18:19], 1.0 op_sel_hi:[1,0]
	v_pk_add_f32 v[20:21], v[20:21], 1.0 op_sel_hi:[1,0]
	v_pk_add_f32 v[12:13], v[12:13], 1.0 op_sel_hi:[1,0]
	v_rcp_f32_e32 v16, v16
	v_rcp_f32_e32 v17, v17
	v_rcp_f32_e32 v18, v18
	v_rcp_f32_e32 v19, v19
	v_rcp_f32_e32 v20, v20
	v_rcp_f32_e32 v21, v21
	v_rcp_f32_e32 v12, v12
	v_rcp_f32_e32 v13, v13
	v_pk_mul_f32 v[16:17], v[14:15], v[16:17] op_sel_hi:[0,1]
	v_pk_mul_f32 v[18:19], v[14:15], v[18:19] op_sel_hi:[0,1]
	v_pk_mul_f32 v[20:21], v[14:15], v[20:21] op_sel_hi:[0,1]
	v_pk_mul_f32 v[12:13], v[14:15], v[12:13] op_sel_hi:[0,1]
	v_pk_mul_f32 v[4:5], v[4:5], v[16:17]
	v_pk_mul_f32 v[14:15], v[2:3], v[18:19]
	v_pk_mul_f32 v[8:9], v[8:9], v[20:21]
	v_pk_mul_f32 v[6:7], v[6:7], v[12:13]
	v_cvt_pk_bf16_f32 v2, v4, v5
	v_cvt_pk_bf16_f32 v3, v14, v15
	v_cvt_pk_bf16_f32 v4, v8, v9
	v_pk_mul_f32 v[8:9], v[100:101], v[96:97]
	v_cvt_pk_bf16_f32 v5, v6, v7
	global_store_dwordx4 v[10:11], v[2:5], off nt
	s_nop 0
	v_lshl_add_u64 v[10:11], v[176:177], 0, s[0:1]
	v_pk_mul_f32 v[4:5], v[104:105], v[108:109]
	v_pk_mul_f32 v[2:3], v[106:107], v[110:111]
	s_add_u32 s0, s48, s0
	s_addc_u32 s1, s49, s1
	s_add_u32 s0, s0, 0x4000
	s_addc_u32 s1, s1, 0
	v_fmamk_f32 v6, v223, 0x3a000000, v200
	v_mul_f32_e32 v7, 0x4b800000, v6
	v_cmp_gt_f32_e32 vcc, s51, v6
	s_nop 1
	v_cndmask_b32_e32 v6, v6, v7, vcc
	v_rsq_f32_e32 v12, v6
	v_pk_mul_f32 v[6:7], v[102:103], v[98:99]
	v_mul_f32_e32 v13, 0x45800000, v12
	v_cndmask_b32_e32 v12, v12, v13, vcc
	v_mul_f32_e32 v13, 0x3b800000, v12
	v_mul_f32_e32 v12, 0xbfb8aa3b, v13
	v_pk_mul_f32 v[16:17], v[104:105], v[12:13] op_sel_hi:[1,0]
	v_mul_f32_e32 v14, v13, v13
	v_pk_mul_f32 v[18:19], v[106:107], v[12:13] op_sel_hi:[1,0]
	v_pk_mul_f32 v[20:21], v[100:101], v[12:13] op_sel_hi:[1,0]
	v_pk_mul_f32 v[12:13], v[102:103], v[12:13] op_sel_hi:[1,0]
	v_exp_f32_e32 v16, v16
	v_exp_f32_e32 v17, v17
	v_exp_f32_e32 v18, v18
	v_exp_f32_e32 v19, v19
	v_exp_f32_e32 v20, v20
	v_exp_f32_e32 v21, v21
	v_exp_f32_e32 v12, v12
	v_exp_f32_e32 v13, v13
	v_pk_add_f32 v[16:17], v[16:17], 1.0 op_sel_hi:[1,0]
	v_pk_add_f32 v[18:19], v[18:19], 1.0 op_sel_hi:[1,0]
	v_pk_add_f32 v[20:21], v[20:21], 1.0 op_sel_hi:[1,0]
	v_pk_add_f32 v[12:13], v[12:13], 1.0 op_sel_hi:[1,0]
	v_rcp_f32_e32 v16, v16
	v_rcp_f32_e32 v17, v17
	v_rcp_f32_e32 v18, v18
	v_rcp_f32_e32 v19, v19
	v_rcp_f32_e32 v20, v20
	v_rcp_f32_e32 v21, v21
	v_rcp_f32_e32 v12, v12
	v_rcp_f32_e32 v13, v13
	v_pk_mul_f32 v[16:17], v[14:15], v[16:17] op_sel_hi:[0,1]
	v_pk_mul_f32 v[18:19], v[14:15], v[18:19] op_sel_hi:[0,1]
	v_pk_mul_f32 v[20:21], v[14:15], v[20:21] op_sel_hi:[0,1]
	v_pk_mul_f32 v[12:13], v[14:15], v[12:13] op_sel_hi:[0,1]
	v_pk_mul_f32 v[4:5], v[4:5], v[16:17]
	v_pk_mul_f32 v[14:15], v[2:3], v[18:19]
	v_pk_mul_f32 v[8:9], v[8:9], v[20:21]
	v_pk_mul_f32 v[6:7], v[6:7], v[12:13]
	v_cvt_pk_bf16_f32 v2, v4, v5
	v_cvt_pk_bf16_f32 v3, v14, v15
	v_cvt_pk_bf16_f32 v4, v8, v9
	v_pk_mul_f32 v[8:9], v[84:85], v[80:81]
	v_cvt_pk_bf16_f32 v5, v6, v7
	global_store_dwordx4 v[10:11], v[2:5], off nt
	s_nop 0
	v_pk_mul_f32 v[6:7], v[86:87], v[82:83]
	v_pk_mul_f32 v[4:5], v[88:89], v[92:93]
	v_pk_mul_f32 v[2:3], v[90:91], v[94:95]
	v_fmamk_f32 v10, v224, 0x3a000000, v200
	v_mul_f32_e32 v11, 0x4b800000, v10
	v_cmp_gt_f32_e32 vcc, s51, v10
	s_nop 1
	v_cndmask_b32_e32 v10, v10, v11, vcc
	v_rsq_f32_e32 v12, v10
	v_lshl_add_u64 v[10:11], v[168:169], 1, s[0:1]
	v_mul_f32_e32 v13, 0x45800000, v12
	v_cndmask_b32_e32 v12, v12, v13, vcc
	v_mul_f32_e32 v13, 0x3b800000, v12
	v_mul_f32_e32 v12, 0xbfb8aa3b, v13
	v_pk_mul_f32 v[16:17], v[88:89], v[12:13] op_sel_hi:[1,0]
	v_mul_f32_e32 v14, v13, v13
	v_pk_mul_f32 v[18:19], v[90:91], v[12:13] op_sel_hi:[1,0]
	v_pk_mul_f32 v[20:21], v[84:85], v[12:13] op_sel_hi:[1,0]
	v_pk_mul_f32 v[12:13], v[86:87], v[12:13] op_sel_hi:[1,0]
	v_exp_f32_e32 v16, v16
	v_exp_f32_e32 v17, v17
	v_exp_f32_e32 v18, v18
	v_exp_f32_e32 v19, v19
	v_exp_f32_e32 v20, v20
	v_exp_f32_e32 v21, v21
	v_exp_f32_e32 v12, v12
	v_exp_f32_e32 v13, v13
	v_pk_add_f32 v[16:17], v[16:17], 1.0 op_sel_hi:[1,0]
	v_pk_add_f32 v[18:19], v[18:19], 1.0 op_sel_hi:[1,0]
	v_pk_add_f32 v[20:21], v[20:21], 1.0 op_sel_hi:[1,0]
	v_pk_add_f32 v[12:13], v[12:13], 1.0 op_sel_hi:[1,0]
	v_rcp_f32_e32 v16, v16
	v_rcp_f32_e32 v17, v17
	v_rcp_f32_e32 v18, v18
	v_rcp_f32_e32 v19, v19
	v_rcp_f32_e32 v20, v20
	v_rcp_f32_e32 v21, v21
	v_rcp_f32_e32 v12, v12
	v_rcp_f32_e32 v13, v13
	v_pk_mul_f32 v[16:17], v[14:15], v[16:17] op_sel_hi:[0,1]
	v_pk_mul_f32 v[18:19], v[14:15], v[18:19] op_sel_hi:[0,1]
	v_pk_mul_f32 v[20:21], v[14:15], v[20:21] op_sel_hi:[0,1]
	v_pk_mul_f32 v[12:13], v[14:15], v[12:13] op_sel_hi:[0,1]
	v_pk_mul_f32 v[4:5], v[4:5], v[16:17]
	v_pk_mul_f32 v[14:15], v[2:3], v[18:19]
	v_pk_mul_f32 v[8:9], v[8:9], v[20:21]
	v_pk_mul_f32 v[6:7], v[6:7], v[12:13]
	v_cvt_pk_bf16_f32 v2, v4, v5
	v_cvt_pk_bf16_f32 v3, v14, v15
	v_cvt_pk_bf16_f32 v4, v8, v9
	v_pk_mul_f32 v[8:9], v[68:69], v[64:65]
	v_cvt_pk_bf16_f32 v5, v6, v7
	global_store_dwordx4 v[10:11], v[2:5], off nt
	s_nop 0
	v_pk_mul_f32 v[6:7], v[70:71], v[66:67]
	v_pk_mul_f32 v[2:3], v[74:75], v[78:79]
	v_fmamk_f32 v4, v225, 0x3a000000, v200
	v_mul_f32_e32 v5, 0x4b800000, v4
	v_cmp_gt_f32_e32 vcc, s51, v4
	s_nop 1
	v_cndmask_b32_e32 v4, v4, v5, vcc
	v_rsq_f32_e32 v10, v4
	v_pk_mul_f32 v[4:5], v[72:73], v[76:77]
	v_mul_f32_e32 v11, 0x45800000, v10
	v_cndmask_b32_e32 v10, v10, v11, vcc
	v_mul_f32_e32 v11, 0x3b800000, v10
	v_mul_f32_e32 v10, 0xbfb8aa3b, v11
	v_pk_mul_f32 v[14:15], v[72:73], v[10:11] op_sel_hi:[1,0]
	v_mul_f32_e32 v12, v11, v11
	v_pk_mul_f32 v[16:17], v[74:75], v[10:11] op_sel_hi:[1,0]
	v_pk_mul_f32 v[18:19], v[68:69], v[10:11] op_sel_hi:[1,0]
	v_pk_mul_f32 v[10:11], v[70:71], v[10:11] op_sel_hi:[1,0]
	v_exp_f32_e32 v14, v14
	v_exp_f32_e32 v15, v15
	v_exp_f32_e32 v16, v16
	v_exp_f32_e32 v17, v17
	v_exp_f32_e32 v18, v18
	v_exp_f32_e32 v19, v19
	v_exp_f32_e32 v10, v10
	v_exp_f32_e32 v11, v11
	v_pk_add_f32 v[14:15], v[14:15], 1.0 op_sel_hi:[1,0]
	v_pk_add_f32 v[16:17], v[16:17], 1.0 op_sel_hi:[1,0]
	v_pk_add_f32 v[18:19], v[18:19], 1.0 op_sel_hi:[1,0]
	v_pk_add_f32 v[10:11], v[10:11], 1.0 op_sel_hi:[1,0]
	v_rcp_f32_e32 v14, v14
	v_rcp_f32_e32 v15, v15
	v_rcp_f32_e32 v16, v16
	v_rcp_f32_e32 v17, v17
	v_rcp_f32_e32 v18, v18
	v_rcp_f32_e32 v19, v19
	v_rcp_f32_e32 v10, v10
	v_rcp_f32_e32 v11, v11
	v_pk_mul_f32 v[14:15], v[12:13], v[14:15] op_sel_hi:[0,1]
	v_pk_mul_f32 v[16:17], v[12:13], v[16:17] op_sel_hi:[0,1]
	v_pk_mul_f32 v[18:19], v[12:13], v[18:19] op_sel_hi:[0,1]
	v_pk_mul_f32 v[10:11], v[12:13], v[10:11] op_sel_hi:[0,1]
	v_pk_mul_f32 v[4:5], v[4:5], v[14:15]
	v_pk_mul_f32 v[12:13], v[2:3], v[16:17]
	v_pk_mul_f32 v[8:9], v[8:9], v[18:19]
	v_pk_mul_f32 v[6:7], v[6:7], v[10:11]
	v_cvt_pk_bf16_f32 v2, v4, v5
	v_cvt_pk_bf16_f32 v3, v12, v13
	v_cvt_pk_bf16_f32 v4, v8, v9
	v_pk_mul_f32 v[8:9], v[52:53], v[48:49]
	v_cvt_pk_bf16_f32 v5, v6, v7
	global_store_dwordx4 v201, v[2:5], s[0:1] nt
	s_nop 0
	v_pk_mul_f32 v[6:7], v[54:55], v[50:51]
	v_pk_mul_f32 v[2:3], v[58:59], v[62:63]
	v_fmamk_f32 v4, v226, 0x3a000000, v200
	v_mul_f32_e32 v5, 0x4b800000, v4
	v_cmp_gt_f32_e32 vcc, s51, v4
	s_nop 1
	v_cndmask_b32_e32 v4, v4, v5, vcc
	v_rsq_f32_e32 v10, v4
	v_pk_mul_f32 v[4:5], v[56:57], v[60:61]
	v_mul_f32_e32 v11, 0x45800000, v10
	v_cndmask_b32_e32 v10, v10, v11, vcc
	v_mul_f32_e32 v11, 0x3b800000, v10
	v_mul_f32_e32 v10, 0xbfb8aa3b, v11
	v_pk_mul_f32 v[14:15], v[56:57], v[10:11] op_sel_hi:[1,0]
	v_mul_f32_e32 v12, v11, v11
	v_pk_mul_f32 v[16:17], v[58:59], v[10:11] op_sel_hi:[1,0]
	v_pk_mul_f32 v[18:19], v[52:53], v[10:11] op_sel_hi:[1,0]
	v_pk_mul_f32 v[10:11], v[54:55], v[10:11] op_sel_hi:[1,0]
	v_exp_f32_e32 v14, v14
	v_exp_f32_e32 v15, v15
	v_exp_f32_e32 v16, v16
	v_exp_f32_e32 v17, v17
	v_exp_f32_e32 v18, v18
	v_exp_f32_e32 v19, v19
	v_exp_f32_e32 v10, v10
	v_exp_f32_e32 v11, v11
	v_pk_add_f32 v[14:15], v[14:15], 1.0 op_sel_hi:[1,0]
	v_pk_add_f32 v[16:17], v[16:17], 1.0 op_sel_hi:[1,0]
	v_pk_add_f32 v[18:19], v[18:19], 1.0 op_sel_hi:[1,0]
	v_pk_add_f32 v[10:11], v[10:11], 1.0 op_sel_hi:[1,0]
	v_rcp_f32_e32 v14, v14
	v_rcp_f32_e32 v15, v15
	v_rcp_f32_e32 v16, v16
	v_rcp_f32_e32 v17, v17
	v_rcp_f32_e32 v18, v18
	v_rcp_f32_e32 v19, v19
	v_rcp_f32_e32 v10, v10
	v_rcp_f32_e32 v11, v11
	v_pk_mul_f32 v[14:15], v[12:13], v[14:15] op_sel_hi:[0,1]
	v_pk_mul_f32 v[16:17], v[12:13], v[16:17] op_sel_hi:[0,1]
	v_pk_mul_f32 v[18:19], v[12:13], v[18:19] op_sel_hi:[0,1]
	v_pk_mul_f32 v[10:11], v[12:13], v[10:11] op_sel_hi:[0,1]
	v_pk_mul_f32 v[4:5], v[4:5], v[14:15]
	v_pk_mul_f32 v[12:13], v[2:3], v[16:17]
	v_pk_mul_f32 v[8:9], v[8:9], v[18:19]
	v_pk_mul_f32 v[6:7], v[6:7], v[10:11]
	v_cvt_pk_bf16_f32 v2, v4, v5
	v_cvt_pk_bf16_f32 v3, v12, v13
	v_cvt_pk_bf16_f32 v4, v8, v9
	s_andn2_b64 vcc, exec, s[4:5]
	v_cvt_pk_bf16_f32 v5, v6, v7
	global_store_dwordx4 v202, v[2:5], s[0:1] nt
	s_nop 0
	v_pk_mul_f32 v[0:1], v[42:43], v[46:47]
	v_pk_mul_f32 v[2:3], v[40:41], v[44:45]
	v_pk_mul_f32 v[4:5], v[34:35], v[38:39]
	v_pk_mul_f32 v[6:7], v[32:33], v[36:37]
	v_fmamk_f32 v8, v227, 0x3a000000, v200
	v_mul_f32_e32 v9, 0x4b800000, v8
	v_cmp_gt_f32_e64 s[6:7], s51, v8
	s_nop 1
	v_cndmask_b32_e64 v8, v8, v9, s[6:7]
	v_rsq_f32_e32 v8, v8
	s_nop 0
	v_mul_f32_e32 v9, 0x45800000, v8
	v_cndmask_b32_e64 v8, v8, v9, s[6:7]
	v_mul_f32_e32 v9, 0x3b800000, v8
	v_mul_f32_e32 v8, 0xbfb8aa3b, v9
	v_pk_mul_f32 v[12:13], v[40:41], v[8:9] op_sel_hi:[1,0]
	v_mul_f32_e32 v10, v9, v9
	v_pk_mul_f32 v[14:15], v[42:43], v[8:9] op_sel_hi:[1,0]
	v_pk_mul_f32 v[16:17], v[32:33], v[8:9] op_sel_hi:[1,0]
	v_pk_mul_f32 v[8:9], v[34:35], v[8:9] op_sel_hi:[1,0]
	v_exp_f32_e32 v12, v12
	v_exp_f32_e32 v13, v13
	v_exp_f32_e32 v14, v14
	v_exp_f32_e32 v15, v15
	v_exp_f32_e32 v16, v16
	v_exp_f32_e32 v17, v17
	v_exp_f32_e32 v8, v8
	v_exp_f32_e32 v9, v9
	v_pk_add_f32 v[12:13], v[12:13], 1.0 op_sel_hi:[1,0]
	v_pk_add_f32 v[14:15], v[14:15], 1.0 op_sel_hi:[1,0]
	v_pk_add_f32 v[16:17], v[16:17], 1.0 op_sel_hi:[1,0]
	v_pk_add_f32 v[8:9], v[8:9], 1.0 op_sel_hi:[1,0]
	v_rcp_f32_e32 v12, v12
	v_rcp_f32_e32 v13, v13
	v_rcp_f32_e32 v14, v14
	v_rcp_f32_e32 v15, v15
	v_rcp_f32_e32 v16, v16
	v_rcp_f32_e32 v17, v17
	v_rcp_f32_e32 v8, v8
	v_rcp_f32_e32 v9, v9
	v_pk_mul_f32 v[12:13], v[10:11], v[12:13] op_sel_hi:[0,1]
	v_pk_mul_f32 v[14:15], v[10:11], v[14:15] op_sel_hi:[0,1]
	v_pk_mul_f32 v[16:17], v[10:11], v[16:17] op_sel_hi:[0,1]
	v_pk_mul_f32 v[8:9], v[10:11], v[8:9] op_sel_hi:[0,1]
	v_pk_mul_f32 v[2:3], v[2:3], v[12:13]
	v_pk_mul_f32 v[10:11], v[0:1], v[14:15]
	v_pk_mul_f32 v[6:7], v[6:7], v[16:17]
	v_pk_mul_f32 v[4:5], v[4:5], v[8:9]
	v_cvt_pk_bf16_f32 v0, v2, v3
	v_cvt_pk_bf16_f32 v1, v10, v11
	v_cvt_pk_bf16_f32 v2, v6, v7
	s_nop 0
	v_cvt_pk_bf16_f32 v3, v4, v5
	global_store_dwordx4 v203, v[0:3], s[0:1] nt
	s_mov_b64 s[0:1], -1
	s_cbranch_vccnz .LBB0_626
	s_andn2_b64 vcc, exec, s[8:9]
	s_cbranch_vccnz .LBB0_625
	s_barrier
	s_branch .LBB0_625
